# attention output (og) stores marked nt: the 134 MB stream no longer passes through L2 beside the shared K/V tiles
# speedup vs baseline: 1.0056x; 1.0040x over previous
.Lopt_done:
	s_mov_b32 s78, 0
	v_and_b32_e32 v79, 64, v191
	v_xor_b32_e32 v78, 32, v191
	v_add_u32_e32 v79, 64, v79
	v_cmp_lt_i32_e32 vcc, v78, v79
	global_load_dwordx4 v[122:125], v[76:77], off offset:3072
	v_ashrrev_i32_e32 v158, 6, v1
	v_cndmask_b32_e32 v78, v191, v78, vcc
	v_lshlrev_b32_e32 v78, 2, v78
	ds_bpermute_b32 v78, v78, v173
	v_add_co_u32_e32 v134, vcc, s37, v74
	v_bfe_u32 v160, v1, 4, 2
	s_nop 0
	v_addc_co_u32_e32 v135, vcc, 0, v75, vcc
	s_waitcnt lgkmcnt(0)
	v_add_f32_e32 v74, v173, v78
	v_div_scale_f32 v75, s[8:9], v74, v74, 1.0
	v_add_co_u32_e32 v136, vcc, s37, v76
	global_load_dwordx4 v[126:129], v[134:135], off
	v_rcp_f32_e32 v76, v75
	v_addc_co_u32_e32 v137, vcc, 0, v77, vcc
	v_div_scale_f32 v77, vcc, 1.0, v74, 1.0
	v_fma_f32 v78, -v75, v76, 1.0
	v_fmac_f32_e32 v76, v78, v76
	v_mul_f32_e32 v78, v77, v76
	v_fma_f32 v79, -v75, v78, v77
	v_fmac_f32_e32 v78, v79, v76
	v_fma_f32 v75, -v75, v78, v77
	v_div_fmas_f32 v75, v75, v76, v78
	v_div_fixup_f32 v138, v75, v74, 1.0
	v_mul_f32_e32 v50, v138, v50
	v_mul_f32_e32 v51, v138, v51
	v_mul_f32_e32 v52, v138, v52
	v_mul_f32_e32 v53, v138, v53
	v_mul_f32_e32 v54, v138, v54
	v_mul_f32_e32 v55, v138, v55
	v_mul_f32_e32 v56, v138, v56
	v_mul_f32_e32 v57, v138, v57
	v_cvt_pk_bf16_f32 v50, v50, v51
	v_cvt_pk_bf16_f32 v51, v52, v53
	v_cvt_pk_bf16_f32 v52, v54, v55
	v_cvt_pk_bf16_f32 v53, v56, v57
	global_load_dwordx4 v[54:57], v[136:137], off
	global_load_dwordx4 v[130:133], v[134:135], off offset:1024
	v_mul_f32_e32 v58, v138, v58
	v_mul_f32_e32 v59, v138, v59
	v_mul_f32_e32 v60, v138, v60
	v_mul_f32_e32 v61, v138, v61
	v_mul_f32_e32 v62, v138, v62
	v_mul_f32_e32 v63, v138, v63
	v_mul_f32_e32 v64, v138, v64
	v_mul_f32_e32 v65, v138, v65
	v_cvt_pk_bf16_f32 v58, v58, v59
	v_cvt_pk_bf16_f32 v59, v60, v61
	v_cvt_pk_bf16_f32 v60, v62, v63
	v_cvt_pk_bf16_f32 v61, v64, v65
	v_mul_f32_e32 v34, v138, v34
	v_mul_f32_e32 v35, v138, v35
	v_mul_f32_e32 v36, v138, v36
	v_mul_f32_e32 v37, v138, v37
	v_mul_f32_e32 v38, v138, v38
	v_mul_f32_e32 v39, v138, v39
	v_mul_f32_e32 v40, v138, v40
	v_mul_f32_e32 v41, v138, v41
	v_mul_f32_e32 v42, v138, v42
	v_mul_f32_e32 v43, v138, v43
	v_mul_f32_e32 v44, v138, v44
	v_mul_f32_e32 v45, v138, v45
	v_mul_f32_e32 v46, v138, v46
	v_mul_f32_e32 v47, v138, v47
	v_mul_f32_e32 v48, v138, v48
	v_mul_f32_e32 v49, v138, v49
	v_mul_f32_e32 v18, v138, v18
	v_mul_f32_e32 v19, v138, v19
	v_mul_f32_e32 v20, v138, v20
	v_mul_f32_e32 v21, v138, v21
	v_mul_f32_e32 v22, v138, v22
	v_mul_f32_e32 v23, v138, v23
	v_mul_f32_e32 v24, v138, v24
	v_mul_f32_e32 v25, v138, v25
	v_mul_f32_e32 v26, v138, v26
	v_mul_f32_e32 v27, v138, v27
	v_mul_f32_e32 v28, v138, v28
	v_mul_f32_e32 v29, v138, v29
	v_mul_f32_e32 v30, v138, v30
	v_mul_f32_e32 v31, v138, v31
	v_mul_f32_e32 v32, v138, v32
	v_mul_f32_e32 v33, v138, v33
	v_mul_f32_e32 v2, v138, v2
	v_mul_f32_e32 v3, v138, v3
	v_mul_f32_e32 v4, v138, v4
	v_mul_f32_e32 v5, v138, v5
	s_waitcnt vmcnt(10)
	v_mfma_f32_32x32x16_bf16 v[82:97], v[66:69], v[50:53], 0
	v_mul_f32_e64 v6, v6, v138
	v_mul_f32_e64 v7, v7, v138
	v_mul_f32_e64 v8, v8, v138
	v_mul_f32_e64 v9, v9, v138
	v_mul_f32_e64 v10, v10, v138
	v_mul_f32_e64 v11, v11, v138
	v_ashrrev_i32_e32 v173, 31, v172
	v_lshlrev_b32_e32 v1, 4, v1
	v_and_b32_e32 v154, 0xf0, v1
	v_mov_b32_e32 v155, v0
	s_waitcnt vmcnt(9)
	v_mfma_f32_32x32x16_bf16 v[66:81], v[70:73], v[50:53], 0
	v_mul_lo_u32 v1, v158, s45
	v_add_u32_e32 v1, 0, v1
	s_mov_b32 s14, 0
	s_waitcnt vmcnt(8)
	v_mfma_f32_32x32x16_bf16 v[82:97], v[102:105], v[58:61], v[82:97]
	global_load_dwordx4 v[62:65], v[134:135], off offset:2048
	global_load_dwordx4 v[102:105], v[134:135], off offset:3072
	s_waitcnt vmcnt(9)
	v_mfma_f32_32x32x16_bf16 v[66:81], v[106:109], v[58:61], v[66:81]
	v_cvt_pk_bf16_f32 v106, v34, v35
	v_cvt_pk_bf16_f32 v107, v36, v37
	v_cvt_pk_bf16_f32 v108, v38, v39
	v_cvt_pk_bf16_f32 v109, v40, v41
	global_load_dwordx4 v[34:37], v[136:137], off offset:1024
	global_load_dwordx4 v[38:41], v[136:137], off offset:2048
	s_waitcnt vmcnt(10)
	v_mfma_f32_32x32x16_bf16 v[82:97], v[110:113], v[106:109], v[82:97]
	v_cvt_pk_bf16_f32 v110, v42, v43
	v_cvt_pk_bf16_f32 v111, v44, v45
	global_load_dwordx4 v[42:45], v[136:137], off offset:3072
	v_cvt_pk_bf16_f32 v112, v46, v47
	v_or_b32_e32 v46, 16, v98
	v_ashrrev_i32_e32 v47, 31, v46
	v_lshlrev_b64 v[46:47], 10, v[46:47]
	v_lshl_add_u64 v[134:135], v[100:101], 0, v[46:47]
	s_waitcnt vmcnt(10)
	v_mfma_f32_32x32x16_bf16 v[66:81], v[114:117], v[106:109], v[66:81]
	v_cvt_pk_bf16_f32 v113, v48, v49
	v_cvt_pk_bf16_f32 v114, v18, v19
	v_cvt_pk_bf16_f32 v115, v20, v21
	v_cvt_pk_bf16_f32 v116, v22, v23
	v_cvt_pk_bf16_f32 v117, v24, v25
	global_load_dwordx4 v[18:21], v[134:135], off
	global_load_dwordx4 v[22:25], v[134:135], off offset:1024
	global_load_dwordx4 v[46:49], v[134:135], off offset:2048
	s_waitcnt vmcnt(12)
	v_mfma_f32_32x32x16_bf16 v[82:97], v[118:121], v[110:113], v[82:97]
	v_cvt_pk_bf16_f32 v118, v26, v27
	v_cvt_pk_bf16_f32 v119, v28, v29
	v_cvt_pk_bf16_f32 v120, v30, v31
	v_cvt_pk_bf16_f32 v121, v32, v33
	global_load_dwordx4 v[26:29], v[134:135], off offset:3072
	s_waitcnt vmcnt(12)
	v_mfma_f32_32x32x16_bf16 v[66:81], v[122:125], v[110:113], v[66:81]
	v_cvt_pk_bf16_f32 v122, v2, v3
	v_cvt_pk_bf16_f32 v123, v4, v5
	v_cvt_pk_bf16_f32 v124, v6, v7
	v_cvt_pk_bf16_f32 v125, v8, v9
	v_mul_f32_e64 v2, v12, v138
	v_mul_f32_e64 v3, v13, v138
	v_mul_f32_e32 v4, v138, v14
	v_mul_f32_e32 v5, v138, v15
	v_mul_f32_e32 v6, v138, v16
	v_mul_f32_e32 v7, v138, v17
	s_waitcnt vmcnt(11)
	v_mfma_f32_32x32x16_bf16 v[82:97], v[126:129], v[114:117], v[82:97]
	s_waitcnt vmcnt(10)
	v_mfma_f32_32x32x16_bf16 v[66:81], v[54:57], v[114:117], v[66:81]
	s_waitcnt vmcnt(9)
	v_mfma_f32_32x32x16_bf16 v[82:97], v[130:133], v[118:121], v[82:97]
	s_waitcnt vmcnt(6)
	v_mfma_f32_32x32x16_bf16 v[66:81], v[34:37], v[118:121], v[66:81]
	v_mfma_f32_32x32x16_bf16 v[82:97], v[62:65], v[122:125], v[82:97]
	v_cvt_pk_bf16_f32 v63, v2, v3
	v_add_co_u32_e32 v2, vcc, s37, v134
	v_cvt_pk_bf16_f32 v62, v10, v11
	s_nop 0
	v_addc_co_u32_e32 v3, vcc, 0, v135, vcc
	global_load_dwordx4 v[30:33], v[2:3], off
	global_load_dwordx4 v[34:37], v[2:3], off offset:1024
	s_waitcnt vmcnt(7)
	v_mfma_f32_32x32x16_bf16 v[66:81], v[38:41], v[122:125], v[66:81]
	v_cvt_pk_bf16_f32 v64, v4, v5
	v_cvt_pk_bf16_f32 v65, v6, v7
	s_waitcnt vmcnt(6)
	s_nop 0
	v_mfma_f32_32x32x16_bf16 v[66:81], v[42:45], v[62:65], v[66:81]
	global_load_dwordx4 v[38:41], v[2:3], off offset:2048
	global_load_dwordx4 v[42:45], v[2:3], off offset:3072
	s_waitcnt vmcnt(7)
	v_mfma_f32_32x32x16_bf16 v[2:17], v[18:21], v[50:53], 0
	v_or_b32_e32 v18, 24, v98
	v_ashrrev_i32_e32 v19, 31, v18
	v_lshlrev_b64 v[18:19], 10, v[18:19]
	v_lshl_add_u64 v[54:55], v[100:101], 0, v[18:19]
	global_load_dwordx4 v[18:21], v[54:55], off
	global_load_dwordx4 v[98:101], v[54:55], off offset:1024
	v_mfma_f32_32x32x16_bf16 v[82:97], v[102:105], v[62:65], v[82:97]
	global_load_dwordx4 v[102:105], v[54:55], off offset:2048
	global_load_dwordx4 v[126:129], v[54:55], off offset:3072
	s_waitcnt vmcnt(10)
	v_mfma_f32_32x32x16_bf16 v[2:17], v[22:25], v[58:61], v[2:17]
	v_add_co_u32_e32 v22, vcc, s37, v54
	v_mov_b32_e32 v24, s55
	s_nop 0
	v_addc_co_u32_e32 v23, vcc, 0, v55, vcc
	global_load_dwordx4 v[130:133], v[22:23], off
	global_load_dwordx4 v[134:137], v[22:23], off offset:1024
	global_load_dwordx4 v[138:141], v[22:23], off offset:2048
	global_load_dwordx4 v[142:145], v[22:23], off offset:3072
	s_waitcnt vmcnt(13)
	v_mfma_f32_32x32x16_bf16 v[2:17], v[46:49], v[106:109], v[2:17]
	v_lshlrev_b32_e32 v22, 5, v158
	v_and_b32_e32 v159, 0x60, v22
	v_lshlrev_b64 v[22:23], 12, v[172:173]
	v_bitop3_b32 v24, v159, s44, v24 bitop3:0xc8
	v_or3_b32 v22, v22, v24, v160
	v_lshlrev_b64 v[22:23], 8, v[22:23]
	s_waitcnt vmcnt(12)
	v_mfma_f32_32x32x16_bf16 v[2:17], v[26:29], v[110:113], v[2:17]
	s_waitcnt vmcnt(11)
	v_mfma_f32_32x32x16_bf16 v[2:17], v[30:33], v[114:117], v[2:17]
	s_waitcnt vmcnt(10)
	v_mfma_f32_32x32x16_bf16 v[2:17], v[34:37], v[118:121], v[2:17]
	v_lshl_add_u64 v[34:35], s[22:23], 0, v[22:23]
	v_lshl_add_u64 v[34:35], v[34:35], 0, v[154:155]
	s_waitcnt vmcnt(7)
	v_mfma_f32_32x32x16_bf16 v[18:33], v[18:21], v[50:53], 0
	global_load_dwordx4 v[146:149], v[34:35], off
	global_load_dwordx4 v[150:153], v[34:35], off offset:1024
	global_load_dwordx4 v[54:57], v[34:35], off offset:2048
	global_load_dwordx4 v[50:53], v[34:35], off offset:3072
	v_add_co_u32_e32 v34, vcc, s37, v34
	s_nop 1
	v_addc_co_u32_e32 v35, vcc, 0, v35, vcc
	s_waitcnt vmcnt(10)
	v_mfma_f32_32x32x16_bf16 v[18:33], v[98:101], v[58:61], v[18:33]
	v_mul_u32_u24_e32 v98, 0x110, v156
	v_lshlrev_b32_e32 v99, 5, v157
	v_cvt_pk_f16_f32 v58, v82, v83
	v_add3_u32 v82, v1, v98, v99
	v_cvt_pk_f16_f32 v59, v84, v85
	v_cvt_pk_f16_f32 v60, v86, v87
	v_cvt_pk_f16_f32 v61, v88, v89
	s_waitcnt vmcnt(9)
	v_mfma_f32_32x32x16_bf16 v[18:33], v[102:105], v[106:109], v[18:33]
	s_waitcnt vmcnt(8)
	v_mfma_f32_32x32x16_bf16 v[18:33], v[126:129], v[110:113], v[18:33]
	s_waitcnt vmcnt(7)
	v_mfma_f32_32x32x16_bf16 v[18:33], v[130:133], v[114:117], v[18:33]
	s_waitcnt vmcnt(6)
	v_mfma_f32_32x32x16_bf16 v[18:33], v[134:137], v[118:121], v[18:33]
	v_mfma_f32_32x32x16_bf16 v[2:17], v[38:41], v[122:125], v[2:17]
	s_waitcnt vmcnt(5)
	v_mfma_f32_32x32x16_bf16 v[18:33], v[138:141], v[122:125], v[18:33]
	v_mfma_f32_32x32x16_bf16 v[2:17], v[42:45], v[62:65], v[2:17]
	global_load_dwordx4 v[46:49], v[34:35], off
	global_load_dwordx4 v[42:45], v[34:35], off offset:1024
	global_load_dwordx4 v[38:41], v[34:35], off offset:2048
	s_nop 0
	global_load_dwordx4 v[34:37], v[34:35], off offset:3072
	ds_write_b128 v82, v[58:61] offset:49152
	v_cvt_pk_f16_f32 v58, v90, v91
	v_cvt_pk_f16_f32 v59, v92, v93
	v_cvt_pk_f16_f32 v60, v94, v95
	v_cvt_pk_f16_f32 v61, v96, v97
	ds_write_b128 v82, v[58:61] offset:49168
	s_waitcnt vmcnt(8)
	v_mfma_f32_32x32x16_bf16 v[18:33], v[142:145], v[62:65], v[18:33]
	v_cvt_pk_f16_f32 v2, v2, v3
	v_cvt_pk_f16_f32 v3, v4, v5
	v_cvt_pk_f16_f32 v4, v6, v7
	v_cvt_pk_f16_f32 v5, v8, v9
	ds_write_b128 v82, v[2:5] offset:49280
	v_cvt_pk_f16_f32 v2, v10, v11
	v_cvt_pk_f16_f32 v3, v12, v13
	v_cvt_pk_f16_f32 v4, v14, v15
	v_cvt_pk_f16_f32 v5, v16, v17
	ds_write_b128 v82, v[2:5] offset:49296
	s_nop 1
	v_cvt_pk_f16_f32 v2, v18, v19
	v_cvt_pk_f16_f32 v3, v20, v21
	v_cvt_pk_f16_f32 v4, v22, v23
	v_cvt_pk_f16_f32 v5, v24, v25
	v_cvt_pk_f16_f32 v58, v66, v67
	v_cvt_pk_f16_f32 v59, v68, v69
	v_cvt_pk_f16_f32 v60, v70, v71
	v_cvt_pk_f16_f32 v61, v72, v73
	ds_write_b128 v82, v[2:5] offset:49344
	v_cvt_pk_f16_f32 v2, v26, v27
	v_cvt_pk_f16_f32 v3, v28, v29
	v_cvt_pk_f16_f32 v4, v30, v31
	v_cvt_pk_f16_f32 v5, v32, v33
	ds_write_b128 v82, v[58:61] offset:49216
	v_cvt_pk_f16_f32 v58, v74, v75
	v_cvt_pk_f16_f32 v59, v76, v77
	v_cvt_pk_f16_f32 v60, v78, v79
	v_cvt_pk_f16_f32 v61, v80, v81
	ds_write_b128 v82, v[2:5] offset:49360
	v_mul_u32_u24_e32 v4, 0x110, v160
	ds_write_b128 v82, v[58:61] offset:49232
	v_add3_u32 v1, v1, v4, v154
	ds_read_b128 v[4:7], v1 offset:49152
	v_or3_b32 v2, v159, s55, v160
	v_mov_b32_e32 v3, v0
	v_lshlrev_b64 v[2:3], 12, v[2:3]
	v_lshlrev_b32_e32 v8, 7, v206
	v_lshl_add_u64 v[2:3], s[18:19], 0, v[2:3]
	v_ashrrev_i32_e32 v9, 31, v8
	v_lshl_add_u64 v[2:3], v[8:9], 1, v[2:3]
	ds_read_b128 v[8:11], v1 offset:50240
	s_waitcnt lgkmcnt(1)
	v_cvt_f32_f16_e32 v12, v4
	v_cvt_f32_f16_sdwa v13, v4 dst_sel:DWORD dst_unused:UNUSED_PAD src0_sel:WORD_1
	s_waitcnt vmcnt(7)
	v_lshlrev_b32_e32 v14, 16, v146
	v_and_b32_e32 v15, 0xffff0000, v146
	v_lshl_add_u64 v[2:3], v[2:3], 0, v[154:155]
	v_mul_f32_e32 v12, v14, v12
	v_mul_f32_e32 v13, v15, v13
	v_cvt_f32_f16_e32 v14, v5
	v_cvt_f32_f16_sdwa v15, v5 dst_sel:DWORD dst_unused:UNUSED_PAD src0_sel:WORD_1
	v_cvt_pk_bf16_f32 v4, v12, v13
	v_lshlrev_b32_e32 v12, 16, v147
	v_and_b32_e32 v13, 0xffff0000, v147
	v_mul_f32_e32 v12, v12, v14
	v_mul_f32_e32 v13, v13, v15
	v_cvt_f32_f16_e32 v14, v6
	v_cvt_f32_f16_sdwa v15, v6 dst_sel:DWORD dst_unused:UNUSED_PAD src0_sel:WORD_1
	v_cvt_pk_bf16_f32 v5, v12, v13
	v_lshlrev_b32_e32 v12, 16, v148
	v_and_b32_e32 v13, 0xffff0000, v148
	v_mul_f32_e32 v12, v12, v14
	v_mul_f32_e32 v13, v13, v15
	v_cvt_f32_f16_e32 v14, v7
	v_cvt_f32_f16_sdwa v15, v7 dst_sel:DWORD dst_unused:UNUSED_PAD src0_sel:WORD_1
	v_cvt_pk_bf16_f32 v6, v12, v13
	v_lshlrev_b32_e32 v12, 16, v149
	v_and_b32_e32 v13, 0xffff0000, v149
	v_mul_f32_e32 v12, v12, v14
	v_mul_f32_e32 v13, v13, v15
	v_add_co_u32_e32 v16, vcc, s16, v2
	v_cvt_pk_bf16_f32 v7, v12, v13
	global_store_dwordx4 v[2:3], v[4:7], off nt
	s_waitcnt lgkmcnt(0)
	v_cvt_f32_f16_e32 v12, v8
	v_cvt_f32_f16_sdwa v13, v8 dst_sel:DWORD dst_unused:UNUSED_PAD src0_sel:WORD_1
	v_cvt_f32_f16_e32 v6, v9
	v_cvt_f32_f16_sdwa v7, v9 dst_sel:DWORD dst_unused:UNUSED_PAD src0_sel:WORD_1
	s_waitcnt vmcnt(7)
	v_lshlrev_b32_e32 v8, 16, v151
	v_and_b32_e32 v9, 0xffff0000, v151
	v_lshlrev_b32_e32 v4, 16, v150
	v_mul_f32_e32 v6, v8, v6
	v_mul_f32_e32 v7, v9, v7
	v_cvt_f32_f16_e32 v8, v10
	v_cvt_f32_f16_sdwa v9, v10 dst_sel:DWORD dst_unused:UNUSED_PAD src0_sel:WORD_1
	v_and_b32_e32 v5, 0xffff0000, v150
	v_mul_f32_e32 v4, v4, v12
	v_mul_f32_e32 v5, v5, v13
	v_lshlrev_b32_e32 v10, 16, v153
	v_cvt_pk_bf16_f32 v4, v4, v5
	v_cvt_pk_bf16_f32 v5, v6, v7
	v_lshlrev_b32_e32 v6, 16, v152
	v_and_b32_e32 v7, 0xffff0000, v152
	v_mul_f32_e32 v6, v6, v8
	v_mul_f32_e32 v7, v7, v9
	v_cvt_f32_f16_e32 v8, v11
	v_cvt_f32_f16_sdwa v9, v11 dst_sel:DWORD dst_unused:UNUSED_PAD src0_sel:WORD_1
	v_and_b32_e32 v11, 0xffff0000, v153
	v_cvt_pk_bf16_f32 v6, v6, v7
	v_addc_co_u32_e32 v17, vcc, 0, v3, vcc
	v_mul_f32_e32 v8, v10, v8
	v_mul_f32_e32 v9, v11, v9
	ds_read_b128 v[12:15], v1 offset:52416
	v_cvt_pk_bf16_f32 v7, v8, v9
	ds_read_b128 v[8:11], v1 offset:51328
	global_store_dwordx4 v[16:17], v[4:7], off nt
	s_waitcnt lgkmcnt(0)
	v_cvt_f32_f16_e32 v18, v8
	v_cvt_f32_f16_e32 v6, v9
	v_cvt_f32_f16_sdwa v7, v9 dst_sel:DWORD dst_unused:UNUSED_PAD src0_sel:WORD_1
	v_cvt_f32_f16_sdwa v19, v8 dst_sel:DWORD dst_unused:UNUSED_PAD src0_sel:WORD_1
	s_waitcnt vmcnt(7)
	v_lshlrev_b32_e32 v8, 16, v55
	v_and_b32_e32 v9, 0xffff0000, v55
	v_mul_f32_e32 v6, v8, v6
	v_mul_f32_e32 v7, v9, v7
	v_cvt_f32_f16_e32 v8, v10
	v_cvt_f32_f16_sdwa v9, v10 dst_sel:DWORD dst_unused:UNUSED_PAD src0_sel:WORD_1
	v_lshlrev_b32_e32 v4, 16, v54
	v_and_b32_e32 v5, 0xffff0000, v54
	v_mul_f32_e32 v4, v4, v18
	v_mul_f32_e32 v5, v5, v19
	v_lshlrev_b32_e32 v10, 16, v57
	v_cvt_pk_bf16_f32 v4, v4, v5
	v_cvt_pk_bf16_f32 v5, v6, v7
	v_lshlrev_b32_e32 v6, 16, v56
	v_and_b32_e32 v7, 0xffff0000, v56
	v_mul_f32_e32 v6, v6, v8
	v_mul_f32_e32 v7, v7, v9
	v_cvt_f32_f16_e32 v8, v11
	v_cvt_f32_f16_sdwa v9, v11 dst_sel:DWORD dst_unused:UNUSED_PAD src0_sel:WORD_1
	v_and_b32_e32 v11, 0xffff0000, v57
	v_cvt_pk_bf16_f32 v6, v6, v7
	v_mul_f32_e32 v8, v10, v8
	v_mul_f32_e32 v9, v11, v9
	s_nop 0
	v_cvt_pk_bf16_f32 v7, v8, v9
	v_add_co_u32_e32 v8, vcc, s41, v2
	v_cvt_f32_f16_e32 v10, v12
	s_nop 0
	v_addc_co_u32_e32 v9, vcc, 0, v3, vcc
	global_store_dwordx4 v[8:9], v[4:7], off nt
	v_cvt_f32_f16_sdwa v11, v12 dst_sel:DWORD dst_unused:UNUSED_PAD src0_sel:WORD_1
	s_waitcnt vmcnt(7)
	v_lshlrev_b32_e32 v8, 16, v51
	v_cvt_f32_f16_e32 v6, v13
	v_cvt_f32_f16_sdwa v7, v13 dst_sel:DWORD dst_unused:UNUSED_PAD src0_sel:WORD_1
	v_and_b32_e32 v9, 0xffff0000, v51
	v_lshlrev_b32_e32 v4, 16, v50
	v_and_b32_e32 v5, 0xffff0000, v50
	v_mul_f32_e32 v6, v8, v6
	v_mul_f32_e32 v7, v9, v7
	v_cvt_f32_f16_e32 v8, v14
	v_cvt_f32_f16_sdwa v9, v14 dst_sel:DWORD dst_unused:UNUSED_PAD src0_sel:WORD_1
	v_mul_f32_e32 v4, v4, v10
	v_mul_f32_e32 v5, v5, v11
	v_lshlrev_b32_e32 v10, 16, v53
	v_cvt_pk_bf16_f32 v4, v4, v5
	v_cvt_pk_bf16_f32 v5, v6, v7
	v_lshlrev_b32_e32 v6, 16, v52
	v_and_b32_e32 v7, 0xffff0000, v52
	v_mul_f32_e32 v6, v6, v8
	v_mul_f32_e32 v7, v7, v9
	v_cvt_f32_f16_e32 v8, v15
	v_cvt_f32_f16_sdwa v9, v15 dst_sel:DWORD dst_unused:UNUSED_PAD src0_sel:WORD_1
	v_and_b32_e32 v11, 0xffff0000, v53
	v_cvt_pk_bf16_f32 v6, v6, v7
	v_add_co_u32_e32 v16, vcc, s50, v2
	v_mul_f32_e32 v8, v10, v8
	v_mul_f32_e32 v9, v11, v9
	s_nop 0
	v_addc_co_u32_e32 v17, vcc, 0, v3, vcc
	v_cvt_pk_bf16_f32 v7, v8, v9
	ds_read_b128 v[8:11], v1 offset:53504
	ds_read_b128 v[12:15], v1 offset:54592
	global_store_dwordx4 v[16:17], v[4:7], off nt
	s_waitcnt lgkmcnt(1)
	v_cvt_f32_f16_e32 v18, v8
	v_cvt_f32_f16_e32 v6, v9
	v_cvt_f32_f16_sdwa v7, v9 dst_sel:DWORD dst_unused:UNUSED_PAD src0_sel:WORD_1
	v_cvt_f32_f16_sdwa v19, v8 dst_sel:DWORD dst_unused:UNUSED_PAD src0_sel:WORD_1
	s_waitcnt vmcnt(7)
	v_lshlrev_b32_e32 v8, 16, v47
	v_and_b32_e32 v9, 0xffff0000, v47
	v_mul_f32_e32 v6, v8, v6
	v_mul_f32_e32 v7, v9, v7
	v_cvt_f32_f16_e32 v8, v10
	v_cvt_f32_f16_sdwa v9, v10 dst_sel:DWORD dst_unused:UNUSED_PAD src0_sel:WORD_1
	v_lshlrev_b32_e32 v4, 16, v46
	v_and_b32_e32 v5, 0xffff0000, v46
	v_mul_f32_e32 v4, v4, v18
	v_mul_f32_e32 v5, v5, v19
	v_lshlrev_b32_e32 v10, 16, v49
	v_cvt_pk_bf16_f32 v4, v4, v5
	v_cvt_pk_bf16_f32 v5, v6, v7
	v_lshlrev_b32_e32 v6, 16, v48
	v_and_b32_e32 v7, 0xffff0000, v48
	v_mul_f32_e32 v6, v6, v8
	v_mul_f32_e32 v7, v7, v9
	v_cvt_f32_f16_e32 v8, v11
	v_cvt_f32_f16_sdwa v9, v11 dst_sel:DWORD dst_unused:UNUSED_PAD src0_sel:WORD_1
	v_and_b32_e32 v11, 0xffff0000, v49
	v_cvt_pk_bf16_f32 v6, v6, v7
	v_mul_f32_e32 v8, v10, v8
	v_mul_f32_e32 v9, v11, v9
	s_nop 0
	v_cvt_pk_bf16_f32 v7, v8, v9
	v_add_co_u32_e32 v8, vcc, s51, v2
	s_waitcnt lgkmcnt(0)
	v_cvt_f32_f16_e32 v10, v12
	v_addc_co_u32_e32 v9, vcc, 0, v3, vcc
	global_store_dwordx4 v[8:9], v[4:7], off nt
	v_cvt_f32_f16_sdwa v11, v12 dst_sel:DWORD dst_unused:UNUSED_PAD src0_sel:WORD_1
	s_waitcnt vmcnt(7)
	v_lshlrev_b32_e32 v8, 16, v43
	v_cvt_f32_f16_e32 v6, v13
	v_cvt_f32_f16_sdwa v7, v13 dst_sel:DWORD dst_unused:UNUSED_PAD src0_sel:WORD_1
	v_and_b32_e32 v9, 0xffff0000, v43
	v_lshlrev_b32_e32 v4, 16, v42
	v_and_b32_e32 v5, 0xffff0000, v42
	v_mul_f32_e32 v6, v8, v6
	v_mul_f32_e32 v7, v9, v7
	v_cvt_f32_f16_e32 v8, v14
	v_cvt_f32_f16_sdwa v9, v14 dst_sel:DWORD dst_unused:UNUSED_PAD src0_sel:WORD_1
	v_mul_f32_e32 v4, v4, v10
	v_mul_f32_e32 v5, v5, v11
	v_lshlrev_b32_e32 v10, 16, v45
	v_cvt_pk_bf16_f32 v4, v4, v5
	v_cvt_pk_bf16_f32 v5, v6, v7
	v_lshlrev_b32_e32 v6, 16, v44
	v_and_b32_e32 v7, 0xffff0000, v44
	v_mul_f32_e32 v6, v6, v8
	v_mul_f32_e32 v7, v7, v9
	v_cvt_f32_f16_e32 v8, v15
	v_cvt_f32_f16_sdwa v9, v15 dst_sel:DWORD dst_unused:UNUSED_PAD src0_sel:WORD_1
	v_and_b32_e32 v11, 0xffff0000, v45
	v_cvt_pk_bf16_f32 v6, v6, v7
	v_add_co_u32_e32 v16, vcc, s52, v2
	v_mul_f32_e32 v8, v10, v8
	v_mul_f32_e32 v9, v11, v9
	s_nop 0
	v_addc_co_u32_e32 v17, vcc, 0, v3, vcc
	v_cvt_pk_bf16_f32 v7, v8, v9
	ds_read_b128 v[8:11], v1 offset:55680
	ds_read_b128 v[12:15], v1 offset:56768
	global_store_dwordx4 v[16:17], v[4:7], off nt
	s_waitcnt lgkmcnt(1)
	v_cvt_f32_f16_e32 v18, v8
	v_cvt_f32_f16_e32 v6, v9
	v_cvt_f32_f16_sdwa v7, v9 dst_sel:DWORD dst_unused:UNUSED_PAD src0_sel:WORD_1
	v_cvt_f32_f16_sdwa v19, v8 dst_sel:DWORD dst_unused:UNUSED_PAD src0_sel:WORD_1
	s_waitcnt vmcnt(7)
	v_lshlrev_b32_e32 v8, 16, v39
	v_and_b32_e32 v9, 0xffff0000, v39
	v_mul_f32_e32 v6, v8, v6
	v_mul_f32_e32 v7, v9, v7
	v_cvt_f32_f16_e32 v8, v10
	v_cvt_f32_f16_sdwa v9, v10 dst_sel:DWORD dst_unused:UNUSED_PAD src0_sel:WORD_1
	v_lshlrev_b32_e32 v4, 16, v38
	v_and_b32_e32 v5, 0xffff0000, v38
	v_mul_f32_e32 v4, v4, v18
	v_mul_f32_e32 v5, v5, v19
	v_lshlrev_b32_e32 v10, 16, v41
	v_cvt_pk_bf16_f32 v4, v4, v5
	v_cvt_pk_bf16_f32 v5, v6, v7
	v_lshlrev_b32_e32 v6, 16, v40
	v_and_b32_e32 v7, 0xffff0000, v40
	v_mul_f32_e32 v6, v6, v8
	v_mul_f32_e32 v7, v7, v9
	v_cvt_f32_f16_e32 v8, v11
	v_cvt_f32_f16_sdwa v9, v11 dst_sel:DWORD dst_unused:UNUSED_PAD src0_sel:WORD_1
	v_and_b32_e32 v11, 0xffff0000, v41
	v_cvt_pk_bf16_f32 v6, v6, v7
	v_mul_f32_e32 v8, v10, v8
	v_mul_f32_e32 v9, v11, v9
	s_nop 0
	v_cvt_pk_bf16_f32 v7, v8, v9
	v_add_co_u32_e32 v8, vcc, s53, v2
	s_waitcnt lgkmcnt(0)
	v_cvt_f32_f16_e32 v10, v12
	v_addc_co_u32_e32 v9, vcc, 0, v3, vcc
	global_store_dwordx4 v[8:9], v[4:7], off nt
	v_cvt_f32_f16_sdwa v11, v12 dst_sel:DWORD dst_unused:UNUSED_PAD src0_sel:WORD_1
	s_waitcnt vmcnt(7)
	v_lshlrev_b32_e32 v8, 16, v35
	v_cvt_f32_f16_e32 v6, v13
	v_cvt_f32_f16_sdwa v7, v13 dst_sel:DWORD dst_unused:UNUSED_PAD src0_sel:WORD_1
	v_and_b32_e32 v9, 0xffff0000, v35
	v_lshlrev_b32_e32 v4, 16, v34
	v_and_b32_e32 v5, 0xffff0000, v34
	v_mul_f32_e32 v6, v8, v6
	v_mul_f32_e32 v7, v9, v7
	v_cvt_f32_f16_e32 v8, v14
	v_cvt_f32_f16_sdwa v9, v14 dst_sel:DWORD dst_unused:UNUSED_PAD src0_sel:WORD_1
	v_mul_f32_e32 v4, v4, v10
	v_mul_f32_e32 v5, v5, v11
	v_lshlrev_b32_e32 v10, 16, v37
	v_cvt_pk_bf16_f32 v4, v4, v5
	v_cvt_pk_bf16_f32 v5, v6, v7
	v_lshlrev_b32_e32 v6, 16, v36
	v_and_b32_e32 v7, 0xffff0000, v36
	v_mul_f32_e32 v6, v6, v8
	v_mul_f32_e32 v7, v7, v9
	v_cvt_f32_f16_e32 v8, v15
	v_cvt_f32_f16_sdwa v9, v15 dst_sel:DWORD dst_unused:UNUSED_PAD src0_sel:WORD_1
	v_and_b32_e32 v11, 0xffff0000, v37
	v_add_co_u32_e32 v2, vcc, 0x1c000, v2
	v_mul_f32_e32 v8, v10, v8
	v_mul_f32_e32 v9, v11, v9
	v_cvt_pk_bf16_f32 v6, v6, v7
	v_cvt_pk_bf16_f32 v7, v8, v9
	v_addc_co_u32_e32 v3, vcc, 0, v3, vcc
	global_store_dwordx4 v[2:3], v[4:7], off nt
